# diff attention: one static s_setprio 1 for the older wave half (waves 0-3) per pass, reset at unit end
# speedup vs baseline: 1.0004x; 1.0004x over previous
.LBB0_490:
	s_mov_b64 s[2:3], s[62:63]
	s_add_u32 s4, s2, s14
	s_addc_u32 s13, s3, s15
	s_lshl_b32 s12, s5, 6
	s_or_b32 s72, s12, s35
	s_lshl_b64 s[10:11], s[72:73], 1
	s_add_u32 s24, s4, s10
	s_addc_u32 s25, s13, s11
	v_lshl_add_u64 v[4:5], s[2:3], 0, v[214:215]
	v_lshl_add_u64 v[6:7], s[2:3], 0, v[216:217]
	s_lshl_b32 s72, s35, 1
	v_lshl_add_u64 v[4:5], v[4:5], 0, s[10:11]
	v_lshl_add_u64 v[6:7], v[6:7], 0, s[72:73]
	v_lshl_add_u64 v[4:5], s[16:17], 1, v[4:5]
	s_mov_b64 s[10:11], 0x8000000
	v_lshl_add_u64 v[6:7], s[18:19], 1, v[6:7]
	s_waitcnt lgkmcnt(0)
	s_barrier
	s_cmp_lt_u32 s30, 0x1000
	s_cbranch_scc0 .Lprio_skip_b
	s_setprio 1
.Lprio_skip_b:
	s_cmp_lg_u32 0, -1
	v_lshl_add_u64 v[36:37], v[4:5], 0, s[10:11]
	v_lshl_add_u64 v[6:7], v[6:7], 0, v[2:3]
	s_mov_b64 s[10:11], 0x10000000
	s_mov_b32 s4, m0
	s_mov_b32 m0, s31
	s_nop 0
	global_load_lds_dwordx4 v[36:37], off
	s_mov_b32 m0, s4
	s_cselect_b32 s13, 0, 0
	v_lshl_add_u64 v[38:39], v[6:7], 0, s[10:11]
	s_mov_b32 s4, m0
	s_mov_b32 m0, s34
	s_nop 0
	global_load_lds_dwordx4 v[38:39], off
	s_mov_b32 m0, s4
	s_mov_b64 s[10:11], 0x10000080
	s_add_i32 s13, s13, s30
	v_lshl_add_u64 v[6:7], v[6:7], 0, s[10:11]
	s_add_i32 s4, s13, 0x8000
	s_mov_b32 s10, m0
	s_mov_b32 m0, s4
	s_nop 0
	global_load_lds_dwordx4 v[6:7], off
	s_mov_b32 m0, s10
	s_mov_b64 s[10:11], 0x8008000
	v_lshl_add_u64 v[6:7], v[4:5], 0, s[10:11]
	v_mov_b32_e32 v229, v3
	s_add_i32 s4, s13, 0x2000
	s_mov_b32 s10, m0
	s_mov_b32 m0, s4
	s_nop 0
	global_load_lds_dwordx4 v[6:7], off
	s_mov_b32 m0, s10
	s_mov_b64 s[10:11], 0x8010000
	v_lshl_add_u64 v[8:9], v[4:5], 0, s[10:11]
	s_add_i32 m0, s13, 0x4000
	s_nop 0
	global_load_lds_dwordx4 v[8:9], off
	v_lshl_add_u64 v[6:7], s[24:25], 0, v[228:229]
	v_mov_b32_e32 v231, v3
	v_lshl_add_u64 v[6:7], v[6:7], 0, v[230:231]
	global_load_dwordx4 v[160:163], v[6:7], off
	global_load_dwordx4 v[156:159], v[6:7], off offset:32
	global_load_dwordx4 v[152:155], v[6:7], off offset:64
	global_load_dwordx4 v[148:151], v[6:7], off offset:96
	s_or_b32 s4, s5, s36
	s_lshl_b32 s4, s4, 1
	s_ashr_i32 s5, s4, 31
	s_lshl_b64 s[4:5], s[4:5], 2
	s_add_u32 s4, s64, s4
	s_addc_u32 s5, s65, s5
	global_load_dwordx2 v[10:11], v3, s[4:5]
	s_mov_b32 s4, 0x3f828f5c
	s_addk_i32 s13, 0x4000
	s_waitcnt vmcnt(0)
	v_and_b32_e32 v7, 0xffff0000, v160
	v_lshlrev_b32_e32 v6, 16, v160
	v_mul_f32_e32 v8, v7, v7
	v_fmac_f32_e32 v8, v6, v6
	v_lshlrev_b32_e32 v6, 16, v161
	v_fmac_f32_e32 v8, v6, v6
	v_and_b32_e32 v6, 0xffff0000, v161
	v_fmac_f32_e32 v8, v6, v6
	v_lshlrev_b32_e32 v6, 16, v162
	v_fmac_f32_e32 v8, v6, v6
	v_and_b32_e32 v6, 0xffff0000, v162
	v_fmac_f32_e32 v8, v6, v6
	v_lshlrev_b32_e32 v6, 16, v163
	v_fmac_f32_e32 v8, v6, v6
	v_and_b32_e32 v6, 0xffff0000, v163
	v_fmac_f32_e32 v8, v6, v6
	v_lshlrev_b32_e32 v6, 16, v156
	v_fmac_f32_e32 v8, v6, v6
	v_and_b32_e32 v6, 0xffff0000, v156
	v_fmac_f32_e32 v8, v6, v6
	v_lshlrev_b32_e32 v6, 16, v157
	v_fmac_f32_e32 v8, v6, v6
	v_and_b32_e32 v6, 0xffff0000, v157
	v_fmac_f32_e32 v8, v6, v6
	v_lshlrev_b32_e32 v6, 16, v158
	v_fmac_f32_e32 v8, v6, v6
	v_and_b32_e32 v6, 0xffff0000, v158
	v_fmac_f32_e32 v8, v6, v6
	v_lshlrev_b32_e32 v6, 16, v159
	v_fmac_f32_e32 v8, v6, v6
	v_and_b32_e32 v6, 0xffff0000, v159
	v_fmac_f32_e32 v8, v6, v6
	v_lshlrev_b32_e32 v6, 16, v152
	v_fmac_f32_e32 v8, v6, v6
	v_and_b32_e32 v6, 0xffff0000, v152
	v_fmac_f32_e32 v8, v6, v6
	v_lshlrev_b32_e32 v6, 16, v153
	v_fmac_f32_e32 v8, v6, v6
	v_and_b32_e32 v6, 0xffff0000, v153
	v_fmac_f32_e32 v8, v6, v6
	v_lshlrev_b32_e32 v6, 16, v154
	v_fmac_f32_e32 v8, v6, v6
	v_and_b32_e32 v6, 0xffff0000, v154
	v_fmac_f32_e32 v8, v6, v6
	v_lshlrev_b32_e32 v6, 16, v155
	v_fmac_f32_e32 v8, v6, v6
	v_and_b32_e32 v6, 0xffff0000, v155
	v_fmac_f32_e32 v8, v6, v6
	v_and_b32_e32 v7, 0xffff0000, v148
	v_lshlrev_b32_e32 v6, 16, v148
	v_pk_mul_f32 v[6:7], v[6:7], v[6:7]
	v_mov_b32_e32 v9, v11
	v_add_f32_e32 v6, v6, v8
	v_add_f32_e32 v8, v7, v6
	v_and_b32_e32 v7, 0xffff0000, v149
	v_lshlrev_b32_e32 v6, 16, v149
	v_pk_mul_f32 v[6:7], v[6:7], v[6:7]
	s_nop 0
	v_add_f32_e32 v6, v6, v8
	v_add_f32_e32 v8, v7, v6
	v_and_b32_e32 v7, 0xffff0000, v150
	v_lshlrev_b32_e32 v6, 16, v150
	v_pk_mul_f32 v[6:7], v[6:7], v[6:7]
	s_nop 0
	v_add_f32_e32 v6, v6, v8
	v_add_f32_e32 v8, v7, v6
	v_and_b32_e32 v7, 0xffff0000, v151
	v_lshlrev_b32_e32 v6, 16, v151
	v_pk_mul_f32 v[6:7], v[6:7], v[6:7]
	s_nop 0
	v_add_f32_e32 v6, v6, v8
	v_add_f32_e32 v6, v7, v6
	v_mov_b32_e32 v8, v6
	s_nop 1
	v_permlane32_swap_b32_e32 v6, v8
	v_mov_b32_e32 v7, v10
	v_pk_add_f32 v[6:7], v[6:7], v[8:9]
	s_nop 0
	v_mul_f32_e32 v6, v6, v7
	v_cmp_gt_f32_e32 vcc, s46, v6
	v_mul_f32_e32 v7, 0x4f800000, v6
	s_nop 0
	v_cndmask_b32_e32 v6, v6, v7, vcc
	v_sqrt_f32_e32 v7, v6
	s_nop 0
	v_add_u32_e32 v8, -1, v7
	v_fma_f32 v9, -v8, v7, v6
	v_cmp_ge_f32_e64 s[10:11], 0, v9
	v_add_u32_e32 v9, 1, v7
	s_nop 0
	v_cndmask_b32_e64 v8, v7, v8, s[10:11]
	v_fma_f32 v7, -v9, v7, v6
	v_cmp_lt_f32_e64 s[10:11], 0, v7
	s_nop 1
	v_cndmask_b32_e64 v7, v8, v9, s[10:11]
	v_mul_f32_e32 v8, 0x37800000, v7
	v_cndmask_b32_e32 v7, v7, v8, vcc
	v_cmp_class_f32_e32 vcc, v6, v244
	s_nop 1
	v_cndmask_b32_e32 v6, v7, v6, vcc
	v_fma_f32 v6, v6, s4, 1.0
	s_mov_b32 s4, 0x42700000
	v_cmp_lt_f32_e32 vcc, s4, v6
	s_waitcnt vmcnt(3) lgkmcnt(0)
	s_barrier
	ds_read_b128 v[4:7], v251
	ds_read_b128 v[20:23], v251 offset:512
	s_waitcnt lgkmcnt(1)
	v_mfma_f32_32x32x16_bf16 v[4:19], v[4:7], v[160:163], 0
	ds_read_b128 v[40:43], v251 offset:2048
	ds_read_b128 v[44:47], v251 offset:2560
	s_cmp_lg_u64 vcc, 0
	s_cselect_b64 s[4:5], -1, 0
	s_waitcnt lgkmcnt(2)
	v_mfma_f32_32x32x16_bf16 v[20:35], v[20:23], v[160:163], 0
	s_waitcnt lgkmcnt(1)
	v_mfma_f32_32x32x16_bf16 v[4:19], v[40:43], v[156:159], v[4:19]
	s_waitcnt lgkmcnt(0)
	v_mfma_f32_32x32x16_bf16 v[20:35], v[44:47], v[156:159], v[20:35]
	ds_read_b128 v[40:43], v251 offset:4096
	ds_read_b128 v[44:47], v251 offset:4608
	s_waitcnt lgkmcnt(1)
	v_mfma_f32_32x32x16_bf16 v[4:19], v[40:43], v[152:155], v[4:19]
	s_waitcnt lgkmcnt(0)
	v_mfma_f32_32x32x16_bf16 v[20:35], v[44:47], v[152:155], v[20:35]
	ds_read_b128 v[40:43], v251 offset:6144
	ds_read_b128 v[44:47], v251 offset:6656
	s_waitcnt lgkmcnt(1)
	v_mfma_f32_32x32x16_bf16 v[4:19], v[40:43], v[148:151], v[4:19]
	s_waitcnt lgkmcnt(0)
	v_mfma_f32_32x32x16_bf16 v[20:35], v[44:47], v[148:151], v[20:35]
	s_cbranch_vccz .LBB0_578
	s_nop 8
	v_max_f32_e32 v40, v5, v5
	v_max_f32_e32 v41, v4, v4
	v_max_f32_e32 v40, v41, v40
	v_max3_f32 v40, v40, v6, v7
	v_max3_f32 v40, v40, v8, v9
	v_max3_f32 v40, v40, v10, v11
	v_max3_f32 v40, v40, v12, v13
	v_max3_f32 v40, v40, v14, v15
	v_max3_f32 v40, v40, v16, v17
	v_max3_f32 v40, v40, v18, v19
	v_max3_f32 v40, v40, v20, v21
	v_max3_f32 v40, v40, v22, v23
	v_max3_f32 v40, v40, v24, v25
	v_max3_f32 v40, v40, v26, v27
	v_max3_f32 v40, v40, v28, v29
	v_max3_f32 v40, v40, v30, v31
	v_max3_f32 v40, v40, v32, v33
	v_max3_f32 v40, v40, v34, v35
	v_mov_b32_e32 v41, v40
	s_nop 1
	v_permlane32_swap_b32_e32 v40, v41
	v_max_f32_e32 v41, v41, v41
	v_max_f32_e32 v40, v40, v40
	v_max_f32_e32 v205, v40, v41
	s_cbranch_execnz .LBB0_493
